# sample attention K-score pass: all 25 key-chunk loads issued up front, dot-product reductions batched 5 at a time (was 25 serial load-wait-reduce round trips)
# speedup vs baseline: 1.0636x; 1.0014x over previous
.LBB0_117:
	s_or_b64 exec, exec, s[6:7]
	s_ashr_i32 s9, s8, 31
	s_lshl_b64 s[6:7], s[8:9], 10
	s_lshl_b32 s28, s20, 7
	s_or_b32 s6, s6, s28
	s_lshl_b64 s[6:7], s[6:7], 2
	s_add_u32 s50, s10, s6
	s_addc_u32 s51, s11, s7
	s_lshl_b64 s[8:9], s[8:9], 23
	s_lshl_b32 s28, s20, 9
	s_add_u32 s40, s44, s8
	s_addc_u32 s41, s45, s9
	s_add_u32 s52, s40, s28
	v_and_b32_e32 v11, 63, v32
	s_waitcnt vmcnt(0)
	v_ashrrev_i32_e32 v37, 5, v32
	s_addc_u32 s53, s41, 0
	s_add_i32 s40, 0, 0x600
	v_and_b32_e32 v35, 31, v32
	v_lshlrev_b32_e32 v12, 2, v11
	v_lshl_add_u32 v39, v37, 2, s40
	v_lshlrev_b32_e32 v0, 2, v35
	v_lshl_add_u32 v13, v35, 4, 0
	v_xor_b32_e32 v10, 64, v12
	v_xor_b32_e32 v9, 32, v12
	v_xor_b32_e32 v8, 16, v12
	v_xor_b32_e32 v3, 8, v12
	v_xor_b32_e32 v1, 4, v12
	s_mov_b32 s30, 0
	v_cmp_eq_u32_e32 vcc, 0, v35
	v_mov_b32_e32 v14, v39
	s_waitcnt lgkmcnt(0)
	s_barrier
	v_mov_b32_e32 v170, v13
	v_mov_b32_e32 v171, 0
	v_lshl_add_u64 v[182:183], s[50:51], 0, v[170:171]
	v_add_u32_e32 v186, 0, v37
	v_mul_hi_i32 v187, v186, s13
	v_lshrrev_b32_e32 v188, 31, v187
	v_ashrrev_i32_e32 v187, 3, v187
	v_add_u32_e32 v187, v187, v188
	v_mad_i32_i24 v188, v187, s16, v186
	v_lshl_add_u32 v144, v187, 9, v13
	v_cmp_eq_u32_e64 s[42:43], 1, v187
	v_cmp_eq_u32_e64 s[56:57], 0, v187
	s_nop 1
	v_cndmask_b32_e64 v189, -16, -4, s[42:43]
	v_cndmask_b32_e64 v189, v189, -1, s[56:57]
	v_mad_i32_i24 v189, v189, v188, v174
	v_cmp_eq_u32_e64 s[42:43], 0, v188
	v_lshlrev_b32_e32 v184, 12, v189
	v_add_u32_e32 v184, v184, v13
	v_mov_b32_e32 v185, 0
	v_lshl_add_u64 v[184:185], s[52:53], 0, v[184:185]
	v_cndmask_b32_e64 v184, v184, v182, s[42:43]
	v_cndmask_b32_e64 v185, v185, v183, s[42:43]
	global_load_dwordx4 v[44:47], v[184:185], off
	v_add_u32_e32 v186, 16, v37
	v_mul_hi_i32 v187, v186, s13
	v_lshrrev_b32_e32 v188, 31, v187
	v_ashrrev_i32_e32 v187, 3, v187
	v_add_u32_e32 v187, v187, v188
	v_mad_i32_i24 v188, v187, s16, v186
	v_lshl_add_u32 v145, v187, 9, v13
	v_cmp_eq_u32_e64 s[42:43], 1, v187
	v_cmp_eq_u32_e64 s[56:57], 0, v187
	s_nop 1
	v_cndmask_b32_e64 v189, -16, -4, s[42:43]
	v_cndmask_b32_e64 v189, v189, -1, s[56:57]
	v_mad_i32_i24 v189, v189, v188, v174
	v_cmp_eq_u32_e64 s[42:43], 0, v188
	v_lshlrev_b32_e32 v184, 12, v189
	v_add_u32_e32 v184, v184, v13
	v_mov_b32_e32 v185, 0
	v_lshl_add_u64 v[184:185], s[52:53], 0, v[184:185]
	v_cndmask_b32_e64 v184, v184, v182, s[42:43]
	v_cndmask_b32_e64 v185, v185, v183, s[42:43]
	global_load_dwordx4 v[48:51], v[184:185], off
	v_add_u32_e32 v186, 32, v37
	v_mul_hi_i32 v187, v186, s13
	v_lshrrev_b32_e32 v188, 31, v187
	v_ashrrev_i32_e32 v187, 3, v187
	v_add_u32_e32 v187, v187, v188
	v_mad_i32_i24 v188, v187, s16, v186
	v_lshl_add_u32 v146, v187, 9, v13
	v_cmp_eq_u32_e64 s[42:43], 1, v187
	v_cmp_eq_u32_e64 s[56:57], 0, v187
	s_nop 1
	v_cndmask_b32_e64 v189, -16, -4, s[42:43]
	v_cndmask_b32_e64 v189, v189, -1, s[56:57]
	v_mad_i32_i24 v189, v189, v188, v174
	v_cmp_eq_u32_e64 s[42:43], 0, v188
	v_lshlrev_b32_e32 v184, 12, v189
	v_add_u32_e32 v184, v184, v13
	v_mov_b32_e32 v185, 0
	v_lshl_add_u64 v[184:185], s[52:53], 0, v[184:185]
	v_cndmask_b32_e64 v184, v184, v182, s[42:43]
	v_cndmask_b32_e64 v185, v185, v183, s[42:43]
	global_load_dwordx4 v[52:55], v[184:185], off
	v_add_u32_e32 v186, 48, v37
	v_mul_hi_i32 v187, v186, s13
	v_lshrrev_b32_e32 v188, 31, v187
	v_ashrrev_i32_e32 v187, 3, v187
	v_add_u32_e32 v187, v187, v188
	v_mad_i32_i24 v188, v187, s16, v186
	v_lshl_add_u32 v147, v187, 9, v13
	v_cmp_eq_u32_e64 s[42:43], 1, v187
	v_cmp_eq_u32_e64 s[56:57], 0, v187
	s_nop 1
	v_cndmask_b32_e64 v189, -16, -4, s[42:43]
	v_cndmask_b32_e64 v189, v189, -1, s[56:57]
	v_mad_i32_i24 v189, v189, v188, v174
	v_cmp_eq_u32_e64 s[42:43], 0, v188
	v_lshlrev_b32_e32 v184, 12, v189
	v_add_u32_e32 v184, v184, v13
	v_mov_b32_e32 v185, 0
	v_lshl_add_u64 v[184:185], s[52:53], 0, v[184:185]
	v_cndmask_b32_e64 v184, v184, v182, s[42:43]
	v_cndmask_b32_e64 v185, v185, v183, s[42:43]
	global_load_dwordx4 v[56:59], v[184:185], off
	v_add_u32_e32 v186, 64, v37
	v_mul_hi_i32 v187, v186, s13
	v_lshrrev_b32_e32 v188, 31, v187
	v_ashrrev_i32_e32 v187, 3, v187
	v_add_u32_e32 v187, v187, v188
	v_mad_i32_i24 v188, v187, s16, v186
	v_lshl_add_u32 v148, v187, 9, v13
	v_cmp_eq_u32_e64 s[42:43], 1, v187
	v_cmp_eq_u32_e64 s[56:57], 0, v187
	s_nop 1
	v_cndmask_b32_e64 v189, -16, -4, s[42:43]
	v_cndmask_b32_e64 v189, v189, -1, s[56:57]
	v_mad_i32_i24 v189, v189, v188, v174
	v_cmp_eq_u32_e64 s[42:43], 0, v188
	v_lshlrev_b32_e32 v184, 12, v189
	v_add_u32_e32 v184, v184, v13
	v_mov_b32_e32 v185, 0
	v_lshl_add_u64 v[184:185], s[52:53], 0, v[184:185]
	v_cndmask_b32_e64 v184, v184, v182, s[42:43]
	v_cndmask_b32_e64 v185, v185, v183, s[42:43]
	global_load_dwordx4 v[60:63], v[184:185], off
	v_add_u32_e32 v186, 0x50, v37
	v_mul_hi_i32 v187, v186, s13
	v_lshrrev_b32_e32 v188, 31, v187
	v_ashrrev_i32_e32 v187, 3, v187
	v_add_u32_e32 v187, v187, v188
	v_mad_i32_i24 v188, v187, s16, v186
	v_lshl_add_u32 v149, v187, 9, v13
	v_cmp_eq_u32_e64 s[42:43], 1, v187
	v_cmp_eq_u32_e64 s[56:57], 0, v187
	s_nop 1
	v_cndmask_b32_e64 v189, -16, -4, s[42:43]
	v_cndmask_b32_e64 v189, v189, -1, s[56:57]
	v_mad_i32_i24 v189, v189, v188, v174
	v_cmp_eq_u32_e64 s[42:43], 0, v188
	v_lshlrev_b32_e32 v184, 12, v189
	v_add_u32_e32 v184, v184, v13
	v_mov_b32_e32 v185, 0
	v_lshl_add_u64 v[184:185], s[52:53], 0, v[184:185]
	v_cndmask_b32_e64 v184, v184, v182, s[42:43]
	v_cndmask_b32_e64 v185, v185, v183, s[42:43]
	global_load_dwordx4 v[64:67], v[184:185], off
	v_add_u32_e32 v186, 0x60, v37
	v_mul_hi_i32 v187, v186, s13
	v_lshrrev_b32_e32 v188, 31, v187
	v_ashrrev_i32_e32 v187, 3, v187
	v_add_u32_e32 v187, v187, v188
	v_mad_i32_i24 v188, v187, s16, v186
	v_lshl_add_u32 v150, v187, 9, v13
	v_cmp_eq_u32_e64 s[42:43], 1, v187
	v_cmp_eq_u32_e64 s[56:57], 0, v187
	s_nop 1
	v_cndmask_b32_e64 v189, -16, -4, s[42:43]
	v_cndmask_b32_e64 v189, v189, -1, s[56:57]
	v_mad_i32_i24 v189, v189, v188, v174
	v_cmp_eq_u32_e64 s[42:43], 0, v188
	v_lshlrev_b32_e32 v184, 12, v189
	v_add_u32_e32 v184, v184, v13
	v_mov_b32_e32 v185, 0
	v_lshl_add_u64 v[184:185], s[52:53], 0, v[184:185]
	v_cndmask_b32_e64 v184, v184, v182, s[42:43]
	v_cndmask_b32_e64 v185, v185, v183, s[42:43]
	global_load_dwordx4 v[68:71], v[184:185], off
	v_add_u32_e32 v186, 0x70, v37
	v_mul_hi_i32 v187, v186, s13
	v_lshrrev_b32_e32 v188, 31, v187
	v_ashrrev_i32_e32 v187, 3, v187
	v_add_u32_e32 v187, v187, v188
	v_mad_i32_i24 v188, v187, s16, v186
	v_lshl_add_u32 v151, v187, 9, v13
	v_cmp_eq_u32_e64 s[42:43], 1, v187
	v_cmp_eq_u32_e64 s[56:57], 0, v187
	s_nop 1
	v_cndmask_b32_e64 v189, -16, -4, s[42:43]
	v_cndmask_b32_e64 v189, v189, -1, s[56:57]
	v_mad_i32_i24 v189, v189, v188, v174
	v_cmp_eq_u32_e64 s[42:43], 0, v188
	v_lshlrev_b32_e32 v184, 12, v189
	v_add_u32_e32 v184, v184, v13
	v_mov_b32_e32 v185, 0
	v_lshl_add_u64 v[184:185], s[52:53], 0, v[184:185]
	v_cndmask_b32_e64 v184, v184, v182, s[42:43]
	v_cndmask_b32_e64 v185, v185, v183, s[42:43]
	global_load_dwordx4 v[72:75], v[184:185], off
	v_add_u32_e32 v186, 0x80, v37
	v_mul_hi_i32 v187, v186, s13
	v_lshrrev_b32_e32 v188, 31, v187
	v_ashrrev_i32_e32 v187, 3, v187
	v_add_u32_e32 v187, v187, v188
	v_mad_i32_i24 v188, v187, s16, v186
	v_lshl_add_u32 v152, v187, 9, v13
	v_cmp_eq_u32_e64 s[42:43], 1, v187
	v_cmp_eq_u32_e64 s[56:57], 0, v187
	s_nop 1
	v_cndmask_b32_e64 v189, -16, -4, s[42:43]
	v_cndmask_b32_e64 v189, v189, -1, s[56:57]
	v_mad_i32_i24 v189, v189, v188, v174
	v_cmp_eq_u32_e64 s[42:43], 0, v188
	v_lshlrev_b32_e32 v184, 12, v189
	v_add_u32_e32 v184, v184, v13
	v_mov_b32_e32 v185, 0
	v_lshl_add_u64 v[184:185], s[52:53], 0, v[184:185]
	v_cndmask_b32_e64 v184, v184, v182, s[42:43]
	v_cndmask_b32_e64 v185, v185, v183, s[42:43]
	global_load_dwordx4 v[76:79], v[184:185], off
	v_add_u32_e32 v186, 0x90, v37
	v_mul_hi_i32 v187, v186, s13
	v_lshrrev_b32_e32 v188, 31, v187
	v_ashrrev_i32_e32 v187, 3, v187
	v_add_u32_e32 v187, v187, v188
	v_mad_i32_i24 v188, v187, s16, v186
	v_lshl_add_u32 v153, v187, 9, v13
	v_cmp_eq_u32_e64 s[42:43], 1, v187
	v_cmp_eq_u32_e64 s[56:57], 0, v187
	s_nop 1
	v_cndmask_b32_e64 v189, -16, -4, s[42:43]
	v_cndmask_b32_e64 v189, v189, -1, s[56:57]
	v_mad_i32_i24 v189, v189, v188, v174
	v_cmp_eq_u32_e64 s[42:43], 0, v188
	v_lshlrev_b32_e32 v184, 12, v189
	v_add_u32_e32 v184, v184, v13
	v_mov_b32_e32 v185, 0
	v_lshl_add_u64 v[184:185], s[52:53], 0, v[184:185]
	v_cndmask_b32_e64 v184, v184, v182, s[42:43]
	v_cndmask_b32_e64 v185, v185, v183, s[42:43]
	global_load_dwordx4 v[80:83], v[184:185], off
	v_add_u32_e32 v186, 0xa0, v37
	v_mul_hi_i32 v187, v186, s13
	v_lshrrev_b32_e32 v188, 31, v187
	v_ashrrev_i32_e32 v187, 3, v187
	v_add_u32_e32 v187, v187, v188
	v_mad_i32_i24 v188, v187, s16, v186
	v_lshl_add_u32 v154, v187, 9, v13
	v_cmp_eq_u32_e64 s[42:43], 1, v187
	v_cmp_eq_u32_e64 s[56:57], 0, v187
	s_nop 1
	v_cndmask_b32_e64 v189, -16, -4, s[42:43]
	v_cndmask_b32_e64 v189, v189, -1, s[56:57]
	v_mad_i32_i24 v189, v189, v188, v174
	v_cmp_eq_u32_e64 s[42:43], 0, v188
	v_lshlrev_b32_e32 v184, 12, v189
	v_add_u32_e32 v184, v184, v13
	v_mov_b32_e32 v185, 0
	v_lshl_add_u64 v[184:185], s[52:53], 0, v[184:185]
	v_cndmask_b32_e64 v184, v184, v182, s[42:43]
	v_cndmask_b32_e64 v185, v185, v183, s[42:43]
	global_load_dwordx4 v[84:87], v[184:185], off
	v_add_u32_e32 v186, 0xb0, v37
	v_mul_hi_i32 v187, v186, s13
	v_lshrrev_b32_e32 v188, 31, v187
	v_ashrrev_i32_e32 v187, 3, v187
	v_add_u32_e32 v187, v187, v188
	v_mad_i32_i24 v188, v187, s16, v186
	v_lshl_add_u32 v155, v187, 9, v13
	v_cmp_eq_u32_e64 s[42:43], 1, v187
	v_cmp_eq_u32_e64 s[56:57], 0, v187
	s_nop 1
	v_cndmask_b32_e64 v189, -16, -4, s[42:43]
	v_cndmask_b32_e64 v189, v189, -1, s[56:57]
	v_mad_i32_i24 v189, v189, v188, v174
	v_cmp_eq_u32_e64 s[42:43], 0, v188
	v_lshlrev_b32_e32 v184, 12, v189
	v_add_u32_e32 v184, v184, v13
	v_mov_b32_e32 v185, 0
	v_lshl_add_u64 v[184:185], s[52:53], 0, v[184:185]
	v_cndmask_b32_e64 v184, v184, v182, s[42:43]
	v_cndmask_b32_e64 v185, v185, v183, s[42:43]
	global_load_dwordx4 v[88:91], v[184:185], off
	v_add_u32_e32 v186, 0xc0, v37
	v_mul_hi_i32 v187, v186, s13
	v_lshrrev_b32_e32 v188, 31, v187
	v_ashrrev_i32_e32 v187, 3, v187
	v_add_u32_e32 v187, v187, v188
	v_mad_i32_i24 v188, v187, s16, v186
	v_lshl_add_u32 v156, v187, 9, v13
	v_cmp_eq_u32_e64 s[42:43], 1, v187
	v_cmp_eq_u32_e64 s[56:57], 0, v187
	s_nop 1
	v_cndmask_b32_e64 v189, -16, -4, s[42:43]
	v_cndmask_b32_e64 v189, v189, -1, s[56:57]
	v_mad_i32_i24 v189, v189, v188, v174
	v_cmp_eq_u32_e64 s[42:43], 0, v188
	v_lshlrev_b32_e32 v184, 12, v189
	v_add_u32_e32 v184, v184, v13
	v_mov_b32_e32 v185, 0
	v_lshl_add_u64 v[184:185], s[52:53], 0, v[184:185]
	v_cndmask_b32_e64 v184, v184, v182, s[42:43]
	v_cndmask_b32_e64 v185, v185, v183, s[42:43]
	global_load_dwordx4 v[92:95], v[184:185], off
	v_add_u32_e32 v186, 0xd0, v37
	v_mul_hi_i32 v187, v186, s13
	v_lshrrev_b32_e32 v188, 31, v187
	v_ashrrev_i32_e32 v187, 3, v187
	v_add_u32_e32 v187, v187, v188
	v_mad_i32_i24 v188, v187, s16, v186
	v_lshl_add_u32 v157, v187, 9, v13
	v_cmp_eq_u32_e64 s[42:43], 1, v187
	v_cmp_eq_u32_e64 s[56:57], 0, v187
	s_nop 1
	v_cndmask_b32_e64 v189, -16, -4, s[42:43]
	v_cndmask_b32_e64 v189, v189, -1, s[56:57]
	v_mad_i32_i24 v189, v189, v188, v174
	v_cmp_eq_u32_e64 s[42:43], 0, v188
	v_lshlrev_b32_e32 v184, 12, v189
	v_add_u32_e32 v184, v184, v13
	v_mov_b32_e32 v185, 0
	v_lshl_add_u64 v[184:185], s[52:53], 0, v[184:185]
	v_cndmask_b32_e64 v184, v184, v182, s[42:43]
	v_cndmask_b32_e64 v185, v185, v183, s[42:43]
	global_load_dwordx4 v[96:99], v[184:185], off
	v_add_u32_e32 v186, 0xe0, v37
	v_mul_hi_i32 v187, v186, s13
	v_lshrrev_b32_e32 v188, 31, v187
	v_ashrrev_i32_e32 v187, 3, v187
	v_add_u32_e32 v187, v187, v188
	v_mad_i32_i24 v188, v187, s16, v186
	v_lshl_add_u32 v158, v187, 9, v13
	v_cmp_eq_u32_e64 s[42:43], 1, v187
	v_cmp_eq_u32_e64 s[56:57], 0, v187
	s_nop 1
	v_cndmask_b32_e64 v189, -16, -4, s[42:43]
	v_cndmask_b32_e64 v189, v189, -1, s[56:57]
	v_mad_i32_i24 v189, v189, v188, v174
	v_cmp_eq_u32_e64 s[42:43], 0, v188
	v_lshlrev_b32_e32 v184, 12, v189
	v_add_u32_e32 v184, v184, v13
	v_mov_b32_e32 v185, 0
	v_lshl_add_u64 v[184:185], s[52:53], 0, v[184:185]
	v_cndmask_b32_e64 v184, v184, v182, s[42:43]
	v_cndmask_b32_e64 v185, v185, v183, s[42:43]
	global_load_dwordx4 v[100:103], v[184:185], off
	v_add_u32_e32 v186, 0xf0, v37
	v_mul_hi_i32 v187, v186, s13
	v_lshrrev_b32_e32 v188, 31, v187
	v_ashrrev_i32_e32 v187, 3, v187
	v_add_u32_e32 v187, v187, v188
	v_mad_i32_i24 v188, v187, s16, v186
	v_lshl_add_u32 v159, v187, 9, v13
	v_cmp_eq_u32_e64 s[42:43], 1, v187
	v_cmp_eq_u32_e64 s[56:57], 0, v187
	s_nop 1
	v_cndmask_b32_e64 v189, -16, -4, s[42:43]
	v_cndmask_b32_e64 v189, v189, -1, s[56:57]
	v_mad_i32_i24 v189, v189, v188, v174
	v_cmp_eq_u32_e64 s[42:43], 0, v188
	v_lshlrev_b32_e32 v184, 12, v189
	v_add_u32_e32 v184, v184, v13
	v_mov_b32_e32 v185, 0
	v_lshl_add_u64 v[184:185], s[52:53], 0, v[184:185]
	v_cndmask_b32_e64 v184, v184, v182, s[42:43]
	v_cndmask_b32_e64 v185, v185, v183, s[42:43]
	global_load_dwordx4 v[104:107], v[184:185], off
	v_add_u32_e32 v186, 0x100, v37
	v_mul_hi_i32 v187, v186, s13
	v_lshrrev_b32_e32 v188, 31, v187
	v_ashrrev_i32_e32 v187, 3, v187
	v_add_u32_e32 v187, v187, v188
	v_mad_i32_i24 v188, v187, s16, v186
	v_lshl_add_u32 v160, v187, 9, v13
	v_cmp_eq_u32_e64 s[42:43], 1, v187
	v_cmp_eq_u32_e64 s[56:57], 0, v187
	s_nop 1
	v_cndmask_b32_e64 v189, -16, -4, s[42:43]
	v_cndmask_b32_e64 v189, v189, -1, s[56:57]
	v_mad_i32_i24 v189, v189, v188, v174
	v_cmp_eq_u32_e64 s[42:43], 0, v188
	v_lshlrev_b32_e32 v184, 12, v189
	v_add_u32_e32 v184, v184, v13
	v_mov_b32_e32 v185, 0
	v_lshl_add_u64 v[184:185], s[52:53], 0, v[184:185]
	v_cndmask_b32_e64 v184, v184, v182, s[42:43]
	v_cndmask_b32_e64 v185, v185, v183, s[42:43]
	global_load_dwordx4 v[108:111], v[184:185], off
	v_add_u32_e32 v186, 0x110, v37
	v_mul_hi_i32 v187, v186, s13
	v_lshrrev_b32_e32 v188, 31, v187
	v_ashrrev_i32_e32 v187, 3, v187
	v_add_u32_e32 v187, v187, v188
	v_mad_i32_i24 v188, v187, s16, v186
	v_lshl_add_u32 v161, v187, 9, v13
	v_cmp_eq_u32_e64 s[42:43], 1, v187
	v_cmp_eq_u32_e64 s[56:57], 0, v187
	s_nop 1
	v_cndmask_b32_e64 v189, -16, -4, s[42:43]
	v_cndmask_b32_e64 v189, v189, -1, s[56:57]
	v_mad_i32_i24 v189, v189, v188, v174
	v_cmp_eq_u32_e64 s[42:43], 0, v188
	v_lshlrev_b32_e32 v184, 12, v189
	v_add_u32_e32 v184, v184, v13
	v_mov_b32_e32 v185, 0
	v_lshl_add_u64 v[184:185], s[52:53], 0, v[184:185]
	v_cndmask_b32_e64 v184, v184, v182, s[42:43]
	v_cndmask_b32_e64 v185, v185, v183, s[42:43]
	global_load_dwordx4 v[112:115], v[184:185], off
	v_add_u32_e32 v186, 0x120, v37
	v_mul_hi_i32 v187, v186, s13
	v_lshrrev_b32_e32 v188, 31, v187
	v_ashrrev_i32_e32 v187, 3, v187
	v_add_u32_e32 v187, v187, v188
	v_mad_i32_i24 v188, v187, s16, v186
	v_lshl_add_u32 v162, v187, 9, v13
	v_cmp_eq_u32_e64 s[42:43], 1, v187
	v_cmp_eq_u32_e64 s[56:57], 0, v187
	s_nop 1
	v_cndmask_b32_e64 v189, -16, -4, s[42:43]
	v_cndmask_b32_e64 v189, v189, -1, s[56:57]
	v_mad_i32_i24 v189, v189, v188, v174
	v_cmp_eq_u32_e64 s[42:43], 0, v188
	v_lshlrev_b32_e32 v184, 12, v189
	v_add_u32_e32 v184, v184, v13
	v_mov_b32_e32 v185, 0
	v_lshl_add_u64 v[184:185], s[52:53], 0, v[184:185]
	v_cndmask_b32_e64 v184, v184, v182, s[42:43]
	v_cndmask_b32_e64 v185, v185, v183, s[42:43]
	global_load_dwordx4 v[116:119], v[184:185], off
	v_add_u32_e32 v186, 0x130, v37
	v_mul_hi_i32 v187, v186, s13
	v_lshrrev_b32_e32 v188, 31, v187
	v_ashrrev_i32_e32 v187, 3, v187
	v_add_u32_e32 v187, v187, v188
	v_mad_i32_i24 v188, v187, s16, v186
	v_lshl_add_u32 v163, v187, 9, v13
	v_cmp_eq_u32_e64 s[42:43], 1, v187
	v_cmp_eq_u32_e64 s[56:57], 0, v187
	s_nop 1
	v_cndmask_b32_e64 v189, -16, -4, s[42:43]
	v_cndmask_b32_e64 v189, v189, -1, s[56:57]
	v_mad_i32_i24 v189, v189, v188, v174
	v_cmp_eq_u32_e64 s[42:43], 0, v188
	v_lshlrev_b32_e32 v184, 12, v189
	v_add_u32_e32 v184, v184, v13
	v_mov_b32_e32 v185, 0
	v_lshl_add_u64 v[184:185], s[52:53], 0, v[184:185]
	v_cndmask_b32_e64 v184, v184, v182, s[42:43]
	v_cndmask_b32_e64 v185, v185, v183, s[42:43]
	global_load_dwordx4 v[120:123], v[184:185], off
	v_add_u32_e32 v186, 0x140, v37
	v_mul_hi_i32 v187, v186, s13
	v_lshrrev_b32_e32 v188, 31, v187
	v_ashrrev_i32_e32 v187, 3, v187
	v_add_u32_e32 v187, v187, v188
	v_mad_i32_i24 v188, v187, s16, v186
	v_lshl_add_u32 v164, v187, 9, v13
	v_cmp_eq_u32_e64 s[42:43], 1, v187
	v_cmp_eq_u32_e64 s[56:57], 0, v187
	s_nop 1
	v_cndmask_b32_e64 v189, -16, -4, s[42:43]
	v_cndmask_b32_e64 v189, v189, -1, s[56:57]
	v_mad_i32_i24 v189, v189, v188, v174
	v_cmp_eq_u32_e64 s[42:43], 0, v188
	v_lshlrev_b32_e32 v184, 12, v189
	v_add_u32_e32 v184, v184, v13
	v_mov_b32_e32 v185, 0
	v_lshl_add_u64 v[184:185], s[52:53], 0, v[184:185]
	v_cndmask_b32_e64 v184, v184, v182, s[42:43]
	v_cndmask_b32_e64 v185, v185, v183, s[42:43]
	global_load_dwordx4 v[124:127], v[184:185], off
	v_add_u32_e32 v186, 0x150, v37
	v_mul_hi_i32 v187, v186, s13
	v_lshrrev_b32_e32 v188, 31, v187
	v_ashrrev_i32_e32 v187, 3, v187
	v_add_u32_e32 v187, v187, v188
	v_mad_i32_i24 v188, v187, s16, v186
	v_lshl_add_u32 v165, v187, 9, v13
	v_cmp_eq_u32_e64 s[42:43], 1, v187
	v_cmp_eq_u32_e64 s[56:57], 0, v187
	s_nop 1
	v_cndmask_b32_e64 v189, -16, -4, s[42:43]
	v_cndmask_b32_e64 v189, v189, -1, s[56:57]
	v_mad_i32_i24 v189, v189, v188, v174
	v_cmp_eq_u32_e64 s[42:43], 0, v188
	v_lshlrev_b32_e32 v184, 12, v189
	v_add_u32_e32 v184, v184, v13
	v_mov_b32_e32 v185, 0
	v_lshl_add_u64 v[184:185], s[52:53], 0, v[184:185]
	v_cndmask_b32_e64 v184, v184, v182, s[42:43]
	v_cndmask_b32_e64 v185, v185, v183, s[42:43]
	global_load_dwordx4 v[128:131], v[184:185], off
	v_add_u32_e32 v186, 0x160, v37
	v_mul_hi_i32 v187, v186, s13
	v_lshrrev_b32_e32 v188, 31, v187
	v_ashrrev_i32_e32 v187, 3, v187
	v_add_u32_e32 v187, v187, v188
	v_mad_i32_i24 v188, v187, s16, v186
	v_lshl_add_u32 v166, v187, 9, v13
	v_cmp_eq_u32_e64 s[42:43], 1, v187
	v_cmp_eq_u32_e64 s[56:57], 0, v187
	s_nop 1
	v_cndmask_b32_e64 v189, -16, -4, s[42:43]
	v_cndmask_b32_e64 v189, v189, -1, s[56:57]
	v_mad_i32_i24 v189, v189, v188, v174
	v_cmp_eq_u32_e64 s[42:43], 0, v188
	v_lshlrev_b32_e32 v184, 12, v189
	v_add_u32_e32 v184, v184, v13
	v_mov_b32_e32 v185, 0
	v_lshl_add_u64 v[184:185], s[52:53], 0, v[184:185]
	v_cndmask_b32_e64 v184, v184, v182, s[42:43]
	v_cndmask_b32_e64 v185, v185, v183, s[42:43]
	global_load_dwordx4 v[132:135], v[184:185], off
	v_add_u32_e32 v186, 0x170, v37
	v_mul_hi_i32 v187, v186, s13
	v_lshrrev_b32_e32 v188, 31, v187
	v_ashrrev_i32_e32 v187, 3, v187
	v_add_u32_e32 v187, v187, v188
	v_mad_i32_i24 v188, v187, s16, v186
	v_lshl_add_u32 v167, v187, 9, v13
	v_cmp_eq_u32_e64 s[42:43], 1, v187
	v_cmp_eq_u32_e64 s[56:57], 0, v187
	s_nop 1
	v_cndmask_b32_e64 v189, -16, -4, s[42:43]
	v_cndmask_b32_e64 v189, v189, -1, s[56:57]
	v_mad_i32_i24 v189, v189, v188, v174
	v_cmp_eq_u32_e64 s[42:43], 0, v188
	v_lshlrev_b32_e32 v184, 12, v189
	v_add_u32_e32 v184, v184, v13
	v_mov_b32_e32 v185, 0
	v_lshl_add_u64 v[184:185], s[52:53], 0, v[184:185]
	v_cndmask_b32_e64 v184, v184, v182, s[42:43]
	v_cndmask_b32_e64 v185, v185, v183, s[42:43]
	global_load_dwordx4 v[136:139], v[184:185], off
	v_add_u32_e32 v186, 0x180, v37
	v_cmp_gt_i32_e64 s[40:41], s21, v186
	s_nop 1
	v_cndmask_b32_e64 v186, v226, v186, s[40:41]
	v_mul_hi_i32 v187, v186, s13
	v_lshrrev_b32_e32 v188, 31, v187
	v_ashrrev_i32_e32 v187, 3, v187
	v_add_u32_e32 v187, v187, v188
	v_mad_i32_i24 v188, v187, s16, v186
	v_lshl_add_u32 v168, v187, 9, v13
	v_cmp_eq_u32_e64 s[42:43], 1, v187
	v_cmp_eq_u32_e64 s[56:57], 0, v187
	s_nop 1
	v_cndmask_b32_e64 v189, -16, -4, s[42:43]
	v_cndmask_b32_e64 v189, v189, -1, s[56:57]
	v_mad_i32_i24 v189, v189, v188, v174
	v_cmp_eq_u32_e64 s[42:43], 0, v188
	v_lshlrev_b32_e32 v184, 12, v189
	v_add_u32_e32 v184, v184, v13
	v_mov_b32_e32 v185, 0
	v_lshl_add_u64 v[184:185], s[52:53], 0, v[184:185]
	v_cndmask_b32_e64 v184, v184, v182, s[42:43]
	v_cndmask_b32_e64 v185, v185, v183, s[42:43]
	global_load_dwordx4 v[140:143], v[184:185], off
	ds_read_b128 v[196:199], v144
	ds_read_b128 v[200:203], v145
	ds_read_b128 v[204:207], v146
	ds_read_b128 v[208:211], v147
	ds_read_b128 v[212:215], v148
	s_waitcnt vmcnt(20)
	s_waitcnt lgkmcnt(0)
	v_mul_f32_e32 v216, v45, v197
	v_fmac_f32_e32 v216, v44, v196
	v_fmac_f32_e32 v216, v46, v198
	v_fmac_f32_e32 v216, v47, v199
	v_mul_f32_e32 v217, v49, v201
	v_fmac_f32_e32 v217, v48, v200
	v_fmac_f32_e32 v217, v50, v202
	v_fmac_f32_e32 v217, v51, v203
	v_mul_f32_e32 v218, v53, v205
	v_fmac_f32_e32 v218, v52, v204
	v_fmac_f32_e32 v218, v54, v206
	v_fmac_f32_e32 v218, v55, v207
	v_mul_f32_e32 v219, v57, v209
	v_fmac_f32_e32 v219, v56, v208
	v_fmac_f32_e32 v219, v58, v210
	v_fmac_f32_e32 v219, v59, v211
	v_mul_f32_e32 v220, v61, v213
	v_fmac_f32_e32 v220, v60, v212
	v_fmac_f32_e32 v220, v62, v214
	v_fmac_f32_e32 v220, v63, v215
	ds_bpermute_b32 v186, v10, v216
	ds_bpermute_b32 v187, v10, v217
	ds_bpermute_b32 v188, v10, v218
	ds_bpermute_b32 v189, v10, v219
	ds_bpermute_b32 v190, v10, v220
	s_waitcnt lgkmcnt(0)
	v_add_f32_e32 v216, v216, v186
	v_add_f32_e32 v217, v217, v187
	v_add_f32_e32 v218, v218, v188
	v_add_f32_e32 v219, v219, v189
	v_add_f32_e32 v220, v220, v190
	ds_bpermute_b32 v186, v9, v216
	ds_bpermute_b32 v187, v9, v217
	ds_bpermute_b32 v188, v9, v218
	ds_bpermute_b32 v189, v9, v219
	ds_bpermute_b32 v190, v9, v220
	s_waitcnt lgkmcnt(0)
	v_add_f32_e32 v216, v216, v186
	v_add_f32_e32 v217, v217, v187
	v_add_f32_e32 v218, v218, v188
	v_add_f32_e32 v219, v219, v189
	v_add_f32_e32 v220, v220, v190
	ds_bpermute_b32 v186, v8, v216
	ds_bpermute_b32 v187, v8, v217
	ds_bpermute_b32 v188, v8, v218
	ds_bpermute_b32 v189, v8, v219
	ds_bpermute_b32 v190, v8, v220
	s_waitcnt lgkmcnt(0)
	v_add_f32_e32 v216, v216, v186
	v_add_f32_e32 v217, v217, v187
	v_add_f32_e32 v218, v218, v188
	v_add_f32_e32 v219, v219, v189
	v_add_f32_e32 v220, v220, v190
	ds_bpermute_b32 v186, v3, v216
	ds_bpermute_b32 v187, v3, v217
	ds_bpermute_b32 v188, v3, v218
	ds_bpermute_b32 v189, v3, v219
	ds_bpermute_b32 v190, v3, v220
	s_waitcnt lgkmcnt(0)
	v_add_f32_e32 v216, v216, v186
	v_add_f32_e32 v217, v217, v187
	v_add_f32_e32 v218, v218, v188
	v_add_f32_e32 v219, v219, v189
	v_add_f32_e32 v220, v220, v190
	ds_bpermute_b32 v186, v1, v216
	ds_bpermute_b32 v187, v1, v217
	ds_bpermute_b32 v188, v1, v218
	ds_bpermute_b32 v189, v1, v219
	ds_bpermute_b32 v190, v1, v220
	s_waitcnt lgkmcnt(0)
	v_add_f32_e32 v216, v216, v186
	v_add_f32_e32 v217, v217, v187
	v_add_f32_e32 v218, v218, v188
	v_add_f32_e32 v219, v219, v189
	v_add_f32_e32 v220, v220, v190
	s_and_saveexec_b64 s[40:41], vcc
	ds_write_b32 v39, v216 offset:0
	ds_write_b32 v39, v217 offset:64
	ds_write_b32 v39, v218 offset:128
	ds_write_b32 v39, v219 offset:192
	ds_write_b32 v39, v220 offset:256
	s_or_b64 exec, exec, s[40:41]
	ds_read_b128 v[196:199], v149
	ds_read_b128 v[200:203], v150
	ds_read_b128 v[204:207], v151
	ds_read_b128 v[208:211], v152
	ds_read_b128 v[212:215], v153
	s_waitcnt vmcnt(15)
	s_waitcnt lgkmcnt(0)
	v_mul_f32_e32 v216, v65, v197
	v_fmac_f32_e32 v216, v64, v196
	v_fmac_f32_e32 v216, v66, v198
	v_fmac_f32_e32 v216, v67, v199
	v_mul_f32_e32 v217, v69, v201
	v_fmac_f32_e32 v217, v68, v200
	v_fmac_f32_e32 v217, v70, v202
	v_fmac_f32_e32 v217, v71, v203
	v_mul_f32_e32 v218, v73, v205
	v_fmac_f32_e32 v218, v72, v204
	v_fmac_f32_e32 v218, v74, v206
	v_fmac_f32_e32 v218, v75, v207
	v_mul_f32_e32 v219, v77, v209
	v_fmac_f32_e32 v219, v76, v208
	v_fmac_f32_e32 v219, v78, v210
	v_fmac_f32_e32 v219, v79, v211
	v_mul_f32_e32 v220, v81, v213
	v_fmac_f32_e32 v220, v80, v212
	v_fmac_f32_e32 v220, v82, v214
	v_fmac_f32_e32 v220, v83, v215
	ds_bpermute_b32 v186, v10, v216
	ds_bpermute_b32 v187, v10, v217
	ds_bpermute_b32 v188, v10, v218
	ds_bpermute_b32 v189, v10, v219
	ds_bpermute_b32 v190, v10, v220
	s_waitcnt lgkmcnt(0)
	v_add_f32_e32 v216, v216, v186
	v_add_f32_e32 v217, v217, v187
	v_add_f32_e32 v218, v218, v188
	v_add_f32_e32 v219, v219, v189
	v_add_f32_e32 v220, v220, v190
	ds_bpermute_b32 v186, v9, v216
	ds_bpermute_b32 v187, v9, v217
	ds_bpermute_b32 v188, v9, v218
	ds_bpermute_b32 v189, v9, v219
	ds_bpermute_b32 v190, v9, v220
	s_waitcnt lgkmcnt(0)
	v_add_f32_e32 v216, v216, v186
	v_add_f32_e32 v217, v217, v187
	v_add_f32_e32 v218, v218, v188
	v_add_f32_e32 v219, v219, v189
	v_add_f32_e32 v220, v220, v190
	ds_bpermute_b32 v186, v8, v216
	ds_bpermute_b32 v187, v8, v217
	ds_bpermute_b32 v188, v8, v218
	ds_bpermute_b32 v189, v8, v219
	ds_bpermute_b32 v190, v8, v220
	s_waitcnt lgkmcnt(0)
	v_add_f32_e32 v216, v216, v186
	v_add_f32_e32 v217, v217, v187
	v_add_f32_e32 v218, v218, v188
	v_add_f32_e32 v219, v219, v189
	v_add_f32_e32 v220, v220, v190
	ds_bpermute_b32 v186, v3, v216
	ds_bpermute_b32 v187, v3, v217
	ds_bpermute_b32 v188, v3, v218
	ds_bpermute_b32 v189, v3, v219
	ds_bpermute_b32 v190, v3, v220
	s_waitcnt lgkmcnt(0)
	v_add_f32_e32 v216, v216, v186
	v_add_f32_e32 v217, v217, v187
	v_add_f32_e32 v218, v218, v188
	v_add_f32_e32 v219, v219, v189
	v_add_f32_e32 v220, v220, v190
	ds_bpermute_b32 v186, v1, v216
	ds_bpermute_b32 v187, v1, v217
	ds_bpermute_b32 v188, v1, v218
	ds_bpermute_b32 v189, v1, v219
	ds_bpermute_b32 v190, v1, v220
	s_waitcnt lgkmcnt(0)
	v_add_f32_e32 v216, v216, v186
	v_add_f32_e32 v217, v217, v187
	v_add_f32_e32 v218, v218, v188
	v_add_f32_e32 v219, v219, v189
	v_add_f32_e32 v220, v220, v190
	s_and_saveexec_b64 s[40:41], vcc
	ds_write_b32 v39, v216 offset:320
	ds_write_b32 v39, v217 offset:384
	ds_write_b32 v39, v218 offset:448
	ds_write_b32 v39, v219 offset:512
	ds_write_b32 v39, v220 offset:576
	s_or_b64 exec, exec, s[40:41]
	ds_read_b128 v[196:199], v154
	ds_read_b128 v[200:203], v155
	ds_read_b128 v[204:207], v156
	ds_read_b128 v[208:211], v157
	ds_read_b128 v[212:215], v158
	s_waitcnt vmcnt(10)
	s_waitcnt lgkmcnt(0)
	v_mul_f32_e32 v216, v85, v197
	v_fmac_f32_e32 v216, v84, v196
	v_fmac_f32_e32 v216, v86, v198
	v_fmac_f32_e32 v216, v87, v199
	v_mul_f32_e32 v217, v89, v201
	v_fmac_f32_e32 v217, v88, v200
	v_fmac_f32_e32 v217, v90, v202
	v_fmac_f32_e32 v217, v91, v203
	v_mul_f32_e32 v218, v93, v205
	v_fmac_f32_e32 v218, v92, v204
	v_fmac_f32_e32 v218, v94, v206
	v_fmac_f32_e32 v218, v95, v207
	v_mul_f32_e32 v219, v97, v209
	v_fmac_f32_e32 v219, v96, v208
	v_fmac_f32_e32 v219, v98, v210
	v_fmac_f32_e32 v219, v99, v211
	v_mul_f32_e32 v220, v101, v213
	v_fmac_f32_e32 v220, v100, v212
	v_fmac_f32_e32 v220, v102, v214
	v_fmac_f32_e32 v220, v103, v215
	ds_bpermute_b32 v186, v10, v216
	ds_bpermute_b32 v187, v10, v217
	ds_bpermute_b32 v188, v10, v218
	ds_bpermute_b32 v189, v10, v219
	ds_bpermute_b32 v190, v10, v220
	s_waitcnt lgkmcnt(0)
	v_add_f32_e32 v216, v216, v186
	v_add_f32_e32 v217, v217, v187
	v_add_f32_e32 v218, v218, v188
	v_add_f32_e32 v219, v219, v189
	v_add_f32_e32 v220, v220, v190
	ds_bpermute_b32 v186, v9, v216
	ds_bpermute_b32 v187, v9, v217
	ds_bpermute_b32 v188, v9, v218
	ds_bpermute_b32 v189, v9, v219
	ds_bpermute_b32 v190, v9, v220
	s_waitcnt lgkmcnt(0)
	v_add_f32_e32 v216, v216, v186
	v_add_f32_e32 v217, v217, v187
	v_add_f32_e32 v218, v218, v188
	v_add_f32_e32 v219, v219, v189
	v_add_f32_e32 v220, v220, v190
	ds_bpermute_b32 v186, v8, v216
	ds_bpermute_b32 v187, v8, v217
	ds_bpermute_b32 v188, v8, v218
	ds_bpermute_b32 v189, v8, v219
	ds_bpermute_b32 v190, v8, v220
	s_waitcnt lgkmcnt(0)
	v_add_f32_e32 v216, v216, v186
	v_add_f32_e32 v217, v217, v187
	v_add_f32_e32 v218, v218, v188
	v_add_f32_e32 v219, v219, v189
	v_add_f32_e32 v220, v220, v190
	ds_bpermute_b32 v186, v3, v216
	ds_bpermute_b32 v187, v3, v217
	ds_bpermute_b32 v188, v3, v218
	ds_bpermute_b32 v189, v3, v219
	ds_bpermute_b32 v190, v3, v220
	s_waitcnt lgkmcnt(0)
	v_add_f32_e32 v216, v216, v186
	v_add_f32_e32 v217, v217, v187
	v_add_f32_e32 v218, v218, v188
	v_add_f32_e32 v219, v219, v189
	v_add_f32_e32 v220, v220, v190
	ds_bpermute_b32 v186, v1, v216
	ds_bpermute_b32 v187, v1, v217
	ds_bpermute_b32 v188, v1, v218
	ds_bpermute_b32 v189, v1, v219
	ds_bpermute_b32 v190, v1, v220
	s_waitcnt lgkmcnt(0)
	v_add_f32_e32 v216, v216, v186
	v_add_f32_e32 v217, v217, v187
	v_add_f32_e32 v218, v218, v188
	v_add_f32_e32 v219, v219, v189
	v_add_f32_e32 v220, v220, v190
	s_and_saveexec_b64 s[40:41], vcc
	ds_write_b32 v39, v216 offset:640
	ds_write_b32 v39, v217 offset:704
	ds_write_b32 v39, v218 offset:768
	ds_write_b32 v39, v219 offset:832
	ds_write_b32 v39, v220 offset:896
	s_or_b64 exec, exec, s[40:41]
	ds_read_b128 v[196:199], v159
	ds_read_b128 v[200:203], v160
	ds_read_b128 v[204:207], v161
	ds_read_b128 v[208:211], v162
	ds_read_b128 v[212:215], v163
	s_waitcnt vmcnt(5)
	s_waitcnt lgkmcnt(0)
	v_mul_f32_e32 v216, v105, v197
	v_fmac_f32_e32 v216, v104, v196
	v_fmac_f32_e32 v216, v106, v198
	v_fmac_f32_e32 v216, v107, v199
	v_mul_f32_e32 v217, v109, v201
	v_fmac_f32_e32 v217, v108, v200
	v_fmac_f32_e32 v217, v110, v202
	v_fmac_f32_e32 v217, v111, v203
	v_mul_f32_e32 v218, v113, v205
	v_fmac_f32_e32 v218, v112, v204
	v_fmac_f32_e32 v218, v114, v206
	v_fmac_f32_e32 v218, v115, v207
	v_mul_f32_e32 v219, v117, v209
	v_fmac_f32_e32 v219, v116, v208
	v_fmac_f32_e32 v219, v118, v210
	v_fmac_f32_e32 v219, v119, v211
	v_mul_f32_e32 v220, v121, v213
	v_fmac_f32_e32 v220, v120, v212
	v_fmac_f32_e32 v220, v122, v214
	v_fmac_f32_e32 v220, v123, v215
	ds_bpermute_b32 v186, v10, v216
	ds_bpermute_b32 v187, v10, v217
	ds_bpermute_b32 v188, v10, v218
	ds_bpermute_b32 v189, v10, v219
	ds_bpermute_b32 v190, v10, v220
	s_waitcnt lgkmcnt(0)
	v_add_f32_e32 v216, v216, v186
	v_add_f32_e32 v217, v217, v187
	v_add_f32_e32 v218, v218, v188
	v_add_f32_e32 v219, v219, v189
	v_add_f32_e32 v220, v220, v190
	ds_bpermute_b32 v186, v9, v216
	ds_bpermute_b32 v187, v9, v217
	ds_bpermute_b32 v188, v9, v218
	ds_bpermute_b32 v189, v9, v219
	ds_bpermute_b32 v190, v9, v220
	s_waitcnt lgkmcnt(0)
	v_add_f32_e32 v216, v216, v186
	v_add_f32_e32 v217, v217, v187
	v_add_f32_e32 v218, v218, v188
	v_add_f32_e32 v219, v219, v189
	v_add_f32_e32 v220, v220, v190
	ds_bpermute_b32 v186, v8, v216
	ds_bpermute_b32 v187, v8, v217
	ds_bpermute_b32 v188, v8, v218
	ds_bpermute_b32 v189, v8, v219
	ds_bpermute_b32 v190, v8, v220
	s_waitcnt lgkmcnt(0)
	v_add_f32_e32 v216, v216, v186
	v_add_f32_e32 v217, v217, v187
	v_add_f32_e32 v218, v218, v188
	v_add_f32_e32 v219, v219, v189
	v_add_f32_e32 v220, v220, v190
	ds_bpermute_b32 v186, v3, v216
	ds_bpermute_b32 v187, v3, v217
	ds_bpermute_b32 v188, v3, v218
	ds_bpermute_b32 v189, v3, v219
	ds_bpermute_b32 v190, v3, v220
	s_waitcnt lgkmcnt(0)
	v_add_f32_e32 v216, v216, v186
	v_add_f32_e32 v217, v217, v187
	v_add_f32_e32 v218, v218, v188
	v_add_f32_e32 v219, v219, v189
	v_add_f32_e32 v220, v220, v190
	ds_bpermute_b32 v186, v1, v216
	ds_bpermute_b32 v187, v1, v217
	ds_bpermute_b32 v188, v1, v218
	ds_bpermute_b32 v189, v1, v219
	ds_bpermute_b32 v190, v1, v220
	s_waitcnt lgkmcnt(0)
	v_add_f32_e32 v216, v216, v186
	v_add_f32_e32 v217, v217, v187
	v_add_f32_e32 v218, v218, v188
	v_add_f32_e32 v219, v219, v189
	v_add_f32_e32 v220, v220, v190
	s_and_saveexec_b64 s[40:41], vcc
	ds_write_b32 v39, v216 offset:960
	ds_write_b32 v39, v217 offset:1024
	ds_write_b32 v39, v218 offset:1088
	ds_write_b32 v39, v219 offset:1152
	ds_write_b32 v39, v220 offset:1216
	s_or_b64 exec, exec, s[40:41]
	ds_read_b128 v[196:199], v164
	ds_read_b128 v[200:203], v165
	ds_read_b128 v[204:207], v166
	ds_read_b128 v[208:211], v167
	ds_read_b128 v[212:215], v168
	s_waitcnt vmcnt(0)
	s_waitcnt lgkmcnt(0)
	v_mul_f32_e32 v216, v125, v197
	v_fmac_f32_e32 v216, v124, v196
	v_fmac_f32_e32 v216, v126, v198
	v_fmac_f32_e32 v216, v127, v199
	v_mul_f32_e32 v217, v129, v201
	v_fmac_f32_e32 v217, v128, v200
	v_fmac_f32_e32 v217, v130, v202
	v_fmac_f32_e32 v217, v131, v203
	v_mul_f32_e32 v218, v133, v205
	v_fmac_f32_e32 v218, v132, v204
	v_fmac_f32_e32 v218, v134, v206
	v_fmac_f32_e32 v218, v135, v207
	v_mul_f32_e32 v219, v137, v209
	v_fmac_f32_e32 v219, v136, v208
	v_fmac_f32_e32 v219, v138, v210
	v_fmac_f32_e32 v219, v139, v211
	v_mul_f32_e32 v220, v141, v213
	v_fmac_f32_e32 v220, v140, v212
	v_fmac_f32_e32 v220, v142, v214
	v_fmac_f32_e32 v220, v143, v215
	ds_bpermute_b32 v186, v10, v216
	ds_bpermute_b32 v187, v10, v217
	ds_bpermute_b32 v188, v10, v218
	ds_bpermute_b32 v189, v10, v219
	ds_bpermute_b32 v190, v10, v220
	s_waitcnt lgkmcnt(0)
	v_add_f32_e32 v216, v216, v186
	v_add_f32_e32 v217, v217, v187
	v_add_f32_e32 v218, v218, v188
	v_add_f32_e32 v219, v219, v189
	v_add_f32_e32 v220, v220, v190
	ds_bpermute_b32 v186, v9, v216
	ds_bpermute_b32 v187, v9, v217
	ds_bpermute_b32 v188, v9, v218
	ds_bpermute_b32 v189, v9, v219
	ds_bpermute_b32 v190, v9, v220
	s_waitcnt lgkmcnt(0)
	v_add_f32_e32 v216, v216, v186
	v_add_f32_e32 v217, v217, v187
	v_add_f32_e32 v218, v218, v188
	v_add_f32_e32 v219, v219, v189
	v_add_f32_e32 v220, v220, v190
	ds_bpermute_b32 v186, v8, v216
	ds_bpermute_b32 v187, v8, v217
	ds_bpermute_b32 v188, v8, v218
	ds_bpermute_b32 v189, v8, v219
	ds_bpermute_b32 v190, v8, v220
	s_waitcnt lgkmcnt(0)
	v_add_f32_e32 v216, v216, v186
	v_add_f32_e32 v217, v217, v187
	v_add_f32_e32 v218, v218, v188
	v_add_f32_e32 v219, v219, v189
	v_add_f32_e32 v220, v220, v190
	ds_bpermute_b32 v186, v3, v216
	ds_bpermute_b32 v187, v3, v217
	ds_bpermute_b32 v188, v3, v218
	ds_bpermute_b32 v189, v3, v219
	ds_bpermute_b32 v190, v3, v220
	s_waitcnt lgkmcnt(0)
	v_add_f32_e32 v216, v216, v186
	v_add_f32_e32 v217, v217, v187
	v_add_f32_e32 v218, v218, v188
	v_add_f32_e32 v219, v219, v189
	v_add_f32_e32 v220, v220, v190
	ds_bpermute_b32 v186, v1, v216
	ds_bpermute_b32 v187, v1, v217
	ds_bpermute_b32 v188, v1, v218
	ds_bpermute_b32 v189, v1, v219
	ds_bpermute_b32 v190, v1, v220
	s_waitcnt lgkmcnt(0)
	v_add_f32_e32 v216, v216, v186
	v_add_f32_e32 v217, v217, v187
	v_add_f32_e32 v218, v218, v188
	v_add_f32_e32 v219, v219, v189
	v_add_f32_e32 v220, v220, v190
	s_and_saveexec_b64 s[40:41], vcc
	ds_write_b32 v39, v216 offset:1280
	ds_write_b32 v39, v217 offset:1344
	ds_write_b32 v39, v218 offset:1408
	ds_write_b32 v39, v219 offset:1472
	s_or_b64 exec, exec, s[40:41]
	v_cmp_gt_u32_e64 s[42:43], 3, v37
	s_and_b64 s[42:43], s[42:43], vcc
	s_and_saveexec_b64 s[40:41], s[42:43]
	ds_write_b32 v39, v220 offset:1536
	s_or_b64 exec, exec, s[40:41]
	v_lshlrev_b32_e32 v172, 2, v0
